# SwiGLU epilogue: packed-f32 (v_pk_mul/v_pk_add) form of the hand-written body, same f32 math
# speedup vs baseline: 1.0028x; 1.0028x over previous
; __device__ __forceinline__ unsigned cvt_pk_bf16(float lo, float hi) { unsigned r; asm volatile("v_cvt_pk_bf16_f32 %0, %1, %2" : "=v"(r) : "v"(lo), "v"(hi)); return r; }
; __device__ __forceinline__ float sigmoid_f(float v) { return __builtin_amdgcn_rcpf(1.0f + __expf(-v)); }
;     __device__ __forceinline__ void operator()(const f32x4 (&acc)[2][2][4][2], const Unit& u, int wr, int wc, int fr, int fq) const {
;     ...
; #pragma unroll
;         for (int ai = 0; ai < 2; ++ai)
; #pragma unroll
;             for (int m = 0; m < 4; ++m) { const int row = row0 + ai * HALF + m * 16; const float r = rr[ai][m];
;                 float o[8];
; #pragma unroll
;                 for (int n = 0; n < 2; ++n)
; #pragma unroll
;                     for (int j = 0; j < 4; ++j) { const float g = acc[ai][0][m][n][j] * r, up = acc[ai][1][m][n][j] * r; o[4 * n + j] = g * sigmoid_f(g) * up; }
;                 u32x4 w; w.x = cvt_pk_bf16(o[0], o[1]); w.y = cvt_pk_bf16(o[2], o[3]); w.z = cvt_pk_bf16(o[4], o[5]); w.w = cvt_pk_bf16(o[6], o[7]);
;                 *(u32x4*)(O + (size_t)row * D_FF + col0) = w; }
.LBB0_666:
	v_lshl_or_b32 v143, s51, 7, v161
	v_mov_b32_e32 v166, 1.0
	v_lshlrev_b32_e32 v143, 1, v143
	v_mad_u32_u24 v143, v142, s76, v143
	v_mul_f32_e32 v156, 0xbfb8aa3b, v151
	v_mul_f32_e32 v157, v151, v151
	v_pk_mul_f32 v[152:153], v[126:127], v[156:157] op_sel_hi:[1,0]
	v_pk_mul_f32 v[154:155], v[128:129], v[156:157] op_sel_hi:[1,0]
	v_exp_f32_e32 v152, v152
	v_exp_f32_e32 v153, v153
	v_exp_f32_e32 v154, v154
	v_exp_f32_e32 v155, v155
	v_pk_mul_f32 v[122:123], v[126:127], v[122:123]
	v_pk_mul_f32 v[124:125], v[128:129], v[124:125]
	v_pk_add_f32 v[152:153], v[152:153], v[166:167] op_sel_hi:[1,0]
	v_pk_add_f32 v[154:155], v[154:155], v[166:167] op_sel_hi:[1,0]
	v_rcp_f32_e32 v152, v152
	v_rcp_f32_e32 v153, v153
	v_rcp_f32_e32 v154, v154
	v_rcp_f32_e32 v155, v155
	v_pk_mul_f32 v[152:153], v[152:153], v[156:157] op_sel:[0,1]
	v_pk_mul_f32 v[154:155], v[154:155], v[156:157] op_sel:[0,1]
	v_pk_mul_f32 v[122:123], v[122:123], v[152:153]
	v_pk_mul_f32 v[124:125], v[124:125], v[154:155]
	v_pk_mul_f32 v[152:153], v[118:119], v[156:157] op_sel_hi:[1,0]
	v_pk_mul_f32 v[154:155], v[120:121], v[156:157] op_sel_hi:[1,0]
	v_exp_f32_e32 v152, v152
	v_exp_f32_e32 v153, v153
	v_exp_f32_e32 v154, v154
	v_exp_f32_e32 v155, v155
	v_pk_mul_f32 v[114:115], v[118:119], v[114:115]
	v_pk_mul_f32 v[116:117], v[120:121], v[116:117]
	v_pk_add_f32 v[152:153], v[152:153], v[166:167] op_sel_hi:[1,0]
	v_pk_add_f32 v[154:155], v[154:155], v[166:167] op_sel_hi:[1,0]
	v_rcp_f32_e32 v152, v152
	v_rcp_f32_e32 v153, v153
	v_rcp_f32_e32 v154, v154
	v_rcp_f32_e32 v155, v155
	v_pk_mul_f32 v[152:153], v[152:153], v[156:157] op_sel:[0,1]
	v_pk_mul_f32 v[154:155], v[154:155], v[156:157] op_sel:[0,1]
	v_pk_mul_f32 v[114:115], v[114:115], v[152:153]
	v_pk_mul_f32 v[116:117], v[116:117], v[154:155]
	v_cvt_pk_bf16_f32 v126, v122, v123
	v_cvt_pk_bf16_f32 v127, v124, v125
	v_cvt_pk_bf16_f32 v128, v114, v115
	v_cvt_pk_bf16_f32 v129, v116, v117
	global_store_dwordx4 v143, v[126:129], s[10:11]
	v_mul_f32_e32 v156, 0xbfb8aa3b, v150
	v_mul_f32_e32 v157, v150, v150
	v_pk_mul_f32 v[152:153], v[110:111], v[156:157] op_sel_hi:[1,0]
	v_pk_mul_f32 v[154:155], v[112:113], v[156:157] op_sel_hi:[1,0]
	v_exp_f32_e32 v152, v152
	v_exp_f32_e32 v153, v153
	v_exp_f32_e32 v154, v154
	v_exp_f32_e32 v155, v155
	v_pk_mul_f32 v[106:107], v[110:111], v[106:107]
	v_pk_mul_f32 v[108:109], v[112:113], v[108:109]
	v_pk_add_f32 v[152:153], v[152:153], v[166:167] op_sel_hi:[1,0]
	v_pk_add_f32 v[154:155], v[154:155], v[166:167] op_sel_hi:[1,0]
	v_rcp_f32_e32 v152, v152
	v_rcp_f32_e32 v153, v153
	v_rcp_f32_e32 v154, v154
	v_rcp_f32_e32 v155, v155
	v_pk_mul_f32 v[152:153], v[152:153], v[156:157] op_sel:[0,1]
	v_pk_mul_f32 v[154:155], v[154:155], v[156:157] op_sel:[0,1]
	v_pk_mul_f32 v[106:107], v[106:107], v[152:153]
	v_pk_mul_f32 v[108:109], v[108:109], v[154:155]
	v_pk_mul_f32 v[152:153], v[102:103], v[156:157] op_sel_hi:[1,0]
	v_pk_mul_f32 v[154:155], v[104:105], v[156:157] op_sel_hi:[1,0]
	v_exp_f32_e32 v152, v152
	v_exp_f32_e32 v153, v153
	v_exp_f32_e32 v154, v154
	v_exp_f32_e32 v155, v155
	v_pk_mul_f32 v[98:99], v[102:103], v[98:99]
	v_pk_mul_f32 v[100:101], v[104:105], v[100:101]
	v_pk_add_f32 v[152:153], v[152:153], v[166:167] op_sel_hi:[1,0]
	v_pk_add_f32 v[154:155], v[154:155], v[166:167] op_sel_hi:[1,0]
	v_rcp_f32_e32 v152, v152
	v_rcp_f32_e32 v153, v153
	v_rcp_f32_e32 v154, v154
	v_rcp_f32_e32 v155, v155
	v_pk_mul_f32 v[152:153], v[152:153], v[156:157] op_sel:[0,1]
	v_pk_mul_f32 v[154:155], v[154:155], v[156:157] op_sel:[0,1]
	v_pk_mul_f32 v[98:99], v[98:99], v[152:153]
	v_pk_mul_f32 v[100:101], v[100:101], v[154:155]
	v_cvt_pk_bf16_f32 v110, v106, v107
	v_cvt_pk_bf16_f32 v111, v108, v109
	v_cvt_pk_bf16_f32 v112, v98, v99
	v_cvt_pk_bf16_f32 v113, v100, v101
	v_add_u32_e32 v142, 0x2c000, v143
	global_store_dwordx4 v142, v[110:113], s[10:11]
	v_mul_f32_e32 v156, 0xbfb8aa3b, v149
	v_mul_f32_e32 v157, v149, v149
	v_pk_mul_f32 v[152:153], v[94:95], v[156:157] op_sel_hi:[1,0]
	v_pk_mul_f32 v[154:155], v[96:97], v[156:157] op_sel_hi:[1,0]
	v_exp_f32_e32 v152, v152
	v_exp_f32_e32 v153, v153
	v_exp_f32_e32 v154, v154
	v_exp_f32_e32 v155, v155
	v_pk_mul_f32 v[90:91], v[94:95], v[90:91]
	v_pk_mul_f32 v[92:93], v[96:97], v[92:93]
	v_pk_add_f32 v[152:153], v[152:153], v[166:167] op_sel_hi:[1,0]
	v_pk_add_f32 v[154:155], v[154:155], v[166:167] op_sel_hi:[1,0]
	v_rcp_f32_e32 v152, v152
	v_rcp_f32_e32 v153, v153
	v_rcp_f32_e32 v154, v154
	v_rcp_f32_e32 v155, v155
	v_pk_mul_f32 v[152:153], v[152:153], v[156:157] op_sel:[0,1]
	v_pk_mul_f32 v[154:155], v[154:155], v[156:157] op_sel:[0,1]
	v_pk_mul_f32 v[90:91], v[90:91], v[152:153]
	v_pk_mul_f32 v[92:93], v[92:93], v[154:155]
	v_pk_mul_f32 v[152:153], v[86:87], v[156:157] op_sel_hi:[1,0]
	v_pk_mul_f32 v[154:155], v[88:89], v[156:157] op_sel_hi:[1,0]
	v_exp_f32_e32 v152, v152
	v_exp_f32_e32 v153, v153
	v_exp_f32_e32 v154, v154
	v_exp_f32_e32 v155, v155
	v_pk_mul_f32 v[82:83], v[86:87], v[82:83]
	v_pk_mul_f32 v[84:85], v[88:89], v[84:85]
	v_pk_add_f32 v[152:153], v[152:153], v[166:167] op_sel_hi:[1,0]
	v_pk_add_f32 v[154:155], v[154:155], v[166:167] op_sel_hi:[1,0]
	v_rcp_f32_e32 v152, v152
	v_rcp_f32_e32 v153, v153
	v_rcp_f32_e32 v154, v154
	v_rcp_f32_e32 v155, v155
	v_pk_mul_f32 v[152:153], v[152:153], v[156:157] op_sel:[0,1]
	v_pk_mul_f32 v[154:155], v[154:155], v[156:157] op_sel:[0,1]
	v_pk_mul_f32 v[82:83], v[82:83], v[152:153]
	v_pk_mul_f32 v[84:85], v[84:85], v[154:155]
	v_cvt_pk_bf16_f32 v94, v90, v91
	v_cvt_pk_bf16_f32 v95, v92, v93
	v_cvt_pk_bf16_f32 v96, v82, v83
	v_cvt_pk_bf16_f32 v97, v84, v85
	v_add_u32_e32 v142, 0x58000, v143
	global_store_dwordx4 v142, v[94:97], s[10:11]
; __device__ __forceinline__ unsigned cvt_pk_bf16(float lo, float hi) { unsigned r; asm volatile("v_cvt_pk_bf16_f32 %0, %1, %2" : "=v"(r) : "v"(lo), "v"(hi)); return r; }
; __device__ __forceinline__ float sigmoid_f(float v) { return __builtin_amdgcn_rcpf(1.0f + __expf(-v)); }
;     __device__ __forceinline__ void operator()(const f32x4 (&acc)[2][2][4][2], const Unit& u, int wr, int wc, int fr, int fq) const {
;     ...
;             for (int m = 0; m < 4; ++m) { const int row = row0 + ai * HALF + m * 16; const float r = rr[ai][m];
;                 float o[8];
; #pragma unroll
;                 for (int n = 0; n < 2; ++n)
; #pragma unroll
;                     for (int j = 0; j < 4; ++j) { const float g = acc[ai][0][m][n][j] * r, up = acc[ai][1][m][n][j] * r; o[4 * n + j] = g * sigmoid_f(g) * up; }
;                 u32x4 w; w.x = cvt_pk_bf16(o[0], o[1]); w.y = cvt_pk_bf16(o[2], o[3]); w.z = cvt_pk_bf16(o[4], o[5]); w.w = cvt_pk_bf16(o[6], o[7]);
;                 *(u32x4*)(O + (size_t)row * D_FF + col0) = w; }
	v_mul_f32_e32 v156, 0xbfb8aa3b, v148
	v_mul_f32_e32 v157, v148, v148
	v_pk_mul_f32 v[152:153], v[78:79], v[156:157] op_sel_hi:[1,0]
	v_pk_mul_f32 v[154:155], v[80:81], v[156:157] op_sel_hi:[1,0]
	v_exp_f32_e32 v152, v152
	v_exp_f32_e32 v153, v153
	v_exp_f32_e32 v154, v154
	v_exp_f32_e32 v155, v155
	v_pk_mul_f32 v[74:75], v[78:79], v[74:75]
	v_pk_mul_f32 v[76:77], v[80:81], v[76:77]
	v_pk_add_f32 v[152:153], v[152:153], v[166:167] op_sel_hi:[1,0]
	v_pk_add_f32 v[154:155], v[154:155], v[166:167] op_sel_hi:[1,0]
	v_rcp_f32_e32 v152, v152
	v_rcp_f32_e32 v153, v153
	v_rcp_f32_e32 v154, v154
	v_rcp_f32_e32 v155, v155
	v_pk_mul_f32 v[152:153], v[152:153], v[156:157] op_sel:[0,1]
	v_pk_mul_f32 v[154:155], v[154:155], v[156:157] op_sel:[0,1]
	v_pk_mul_f32 v[74:75], v[74:75], v[152:153]
	v_pk_mul_f32 v[76:77], v[76:77], v[154:155]
	v_pk_mul_f32 v[152:153], v[70:71], v[156:157] op_sel_hi:[1,0]
	v_pk_mul_f32 v[154:155], v[72:73], v[156:157] op_sel_hi:[1,0]
	v_exp_f32_e32 v152, v152
	v_exp_f32_e32 v153, v153
	v_exp_f32_e32 v154, v154
	v_exp_f32_e32 v155, v155
	v_pk_mul_f32 v[66:67], v[70:71], v[66:67]
	v_pk_mul_f32 v[68:69], v[72:73], v[68:69]
	v_pk_add_f32 v[152:153], v[152:153], v[166:167] op_sel_hi:[1,0]
	v_pk_add_f32 v[154:155], v[154:155], v[166:167] op_sel_hi:[1,0]
	v_rcp_f32_e32 v152, v152
	v_rcp_f32_e32 v153, v153
	v_rcp_f32_e32 v154, v154
	v_rcp_f32_e32 v155, v155
	v_pk_mul_f32 v[152:153], v[152:153], v[156:157] op_sel:[0,1]
	v_pk_mul_f32 v[154:155], v[154:155], v[156:157] op_sel:[0,1]
	v_pk_mul_f32 v[66:67], v[66:67], v[152:153]
	v_pk_mul_f32 v[68:69], v[68:69], v[154:155]
	v_cvt_pk_bf16_f32 v78, v74, v75
	v_cvt_pk_bf16_f32 v79, v76, v77
	v_cvt_pk_bf16_f32 v80, v66, v67
	v_cvt_pk_bf16_f32 v81, v68, v69
	v_add_u32_e32 v142, 0x84000, v143
	global_store_dwordx4 v142, v[78:81], s[10:11]
	v_mul_f32_e32 v156, 0xbfb8aa3b, v147
	v_mul_f32_e32 v157, v147, v147
	v_pk_mul_f32 v[152:153], v[62:63], v[156:157] op_sel_hi:[1,0]
	v_pk_mul_f32 v[154:155], v[64:65], v[156:157] op_sel_hi:[1,0]
	v_exp_f32_e32 v152, v152
	v_exp_f32_e32 v153, v153
	v_exp_f32_e32 v154, v154
	v_exp_f32_e32 v155, v155
	v_pk_mul_f32 v[58:59], v[62:63], v[58:59]
	v_pk_mul_f32 v[60:61], v[64:65], v[60:61]
	v_pk_add_f32 v[152:153], v[152:153], v[166:167] op_sel_hi:[1,0]
	v_pk_add_f32 v[154:155], v[154:155], v[166:167] op_sel_hi:[1,0]
	v_rcp_f32_e32 v152, v152
	v_rcp_f32_e32 v153, v153
	v_rcp_f32_e32 v154, v154
	v_rcp_f32_e32 v155, v155
	v_pk_mul_f32 v[152:153], v[152:153], v[156:157] op_sel:[0,1]
	v_pk_mul_f32 v[154:155], v[154:155], v[156:157] op_sel:[0,1]
	v_pk_mul_f32 v[58:59], v[58:59], v[152:153]
	v_pk_mul_f32 v[60:61], v[60:61], v[154:155]
	v_pk_mul_f32 v[152:153], v[54:55], v[156:157] op_sel_hi:[1,0]
	v_pk_mul_f32 v[154:155], v[56:57], v[156:157] op_sel_hi:[1,0]
	v_exp_f32_e32 v152, v152
	v_exp_f32_e32 v153, v153
	v_exp_f32_e32 v154, v154
	v_exp_f32_e32 v155, v155
	v_pk_mul_f32 v[50:51], v[54:55], v[50:51]
	v_pk_mul_f32 v[52:53], v[56:57], v[52:53]
	v_pk_add_f32 v[152:153], v[152:153], v[166:167] op_sel_hi:[1,0]
	v_pk_add_f32 v[154:155], v[154:155], v[166:167] op_sel_hi:[1,0]
	v_rcp_f32_e32 v152, v152
	v_rcp_f32_e32 v153, v153
	v_rcp_f32_e32 v154, v154
	v_rcp_f32_e32 v155, v155
	v_pk_mul_f32 v[152:153], v[152:153], v[156:157] op_sel:[0,1]
	v_pk_mul_f32 v[154:155], v[154:155], v[156:157] op_sel:[0,1]
	v_pk_mul_f32 v[50:51], v[50:51], v[152:153]
	v_pk_mul_f32 v[52:53], v[52:53], v[154:155]
	v_cvt_pk_bf16_f32 v62, v58, v59
	v_cvt_pk_bf16_f32 v63, v60, v61
	v_cvt_pk_bf16_f32 v64, v50, v51
	v_cvt_pk_bf16_f32 v65, v52, v53
	v_add_u32_e32 v142, 0x160000, v143
	global_store_dwordx4 v142, v[62:65], s[10:11]
	v_mul_f32_e32 v156, 0xbfb8aa3b, v146
	v_mul_f32_e32 v157, v146, v146
	v_pk_mul_f32 v[152:153], v[46:47], v[156:157] op_sel_hi:[1,0]
	v_pk_mul_f32 v[154:155], v[48:49], v[156:157] op_sel_hi:[1,0]
	v_exp_f32_e32 v152, v152
	v_exp_f32_e32 v153, v153
	v_exp_f32_e32 v154, v154
	v_exp_f32_e32 v155, v155
	v_pk_mul_f32 v[42:43], v[46:47], v[42:43]
	v_pk_mul_f32 v[44:45], v[48:49], v[44:45]
	v_pk_add_f32 v[152:153], v[152:153], v[166:167] op_sel_hi:[1,0]
	v_pk_add_f32 v[154:155], v[154:155], v[166:167] op_sel_hi:[1,0]
	v_rcp_f32_e32 v152, v152
	v_rcp_f32_e32 v153, v153
	v_rcp_f32_e32 v154, v154
	v_rcp_f32_e32 v155, v155
	v_pk_mul_f32 v[152:153], v[152:153], v[156:157] op_sel:[0,1]
	v_pk_mul_f32 v[154:155], v[154:155], v[156:157] op_sel:[0,1]
	v_pk_mul_f32 v[42:43], v[42:43], v[152:153]
	v_pk_mul_f32 v[44:45], v[44:45], v[154:155]
	v_pk_mul_f32 v[152:153], v[38:39], v[156:157] op_sel_hi:[1,0]
	v_pk_mul_f32 v[154:155], v[40:41], v[156:157] op_sel_hi:[1,0]
	v_exp_f32_e32 v152, v152
; __device__ __forceinline__ unsigned cvt_pk_bf16(float lo, float hi) { unsigned r; asm volatile("v_cvt_pk_bf16_f32 %0, %1, %2" : "=v"(r) : "v"(lo), "v"(hi)); return r; }
; __device__ __forceinline__ float sigmoid_f(float v) { return __builtin_amdgcn_rcpf(1.0f + __expf(-v)); }
;     __device__ __forceinline__ void operator()(const f32x4 (&acc)[2][2][4][2], const Unit& u, int wr, int wc, int fr, int fq) const {
;     ...
;             for (int m = 0; m < 4; ++m) { const int row = row0 + ai * HALF + m * 16; const float r = rr[ai][m];
;                 float o[8];
; #pragma unroll
;                 for (int n = 0; n < 2; ++n)
; #pragma unroll
;                     for (int j = 0; j < 4; ++j) { const float g = acc[ai][0][m][n][j] * r, up = acc[ai][1][m][n][j] * r; o[4 * n + j] = g * sigmoid_f(g) * up; }
;                 u32x4 w; w.x = cvt_pk_bf16(o[0], o[1]); w.y = cvt_pk_bf16(o[2], o[3]); w.z = cvt_pk_bf16(o[4], o[5]); w.w = cvt_pk_bf16(o[6], o[7]);
;                 *(u32x4*)(O + (size_t)row * D_FF + col0) = w; }
	v_exp_f32_e32 v153, v153
	v_exp_f32_e32 v154, v154
	v_exp_f32_e32 v155, v155
	v_pk_mul_f32 v[34:35], v[38:39], v[34:35]
	v_pk_mul_f32 v[36:37], v[40:41], v[36:37]
	v_pk_add_f32 v[152:153], v[152:153], v[166:167] op_sel_hi:[1,0]
	v_pk_add_f32 v[154:155], v[154:155], v[166:167] op_sel_hi:[1,0]
	v_rcp_f32_e32 v152, v152
	v_rcp_f32_e32 v153, v153
	v_rcp_f32_e32 v154, v154
	v_rcp_f32_e32 v155, v155
	v_pk_mul_f32 v[152:153], v[152:153], v[156:157] op_sel:[0,1]
	v_pk_mul_f32 v[154:155], v[154:155], v[156:157] op_sel:[0,1]
	v_pk_mul_f32 v[34:35], v[34:35], v[152:153]
	v_pk_mul_f32 v[36:37], v[36:37], v[154:155]
	v_cvt_pk_bf16_f32 v46, v42, v43
	v_cvt_pk_bf16_f32 v47, v44, v45
	v_cvt_pk_bf16_f32 v48, v34, v35
	v_cvt_pk_bf16_f32 v49, v36, v37
	v_add_u32_e32 v142, 0x18c000, v143
	global_store_dwordx4 v142, v[46:49], s[10:11]
	v_mul_f32_e32 v156, 0xbfb8aa3b, v145
	v_mul_f32_e32 v157, v145, v145
	v_pk_mul_f32 v[152:153], v[30:31], v[156:157] op_sel_hi:[1,0]
	v_pk_mul_f32 v[154:155], v[32:33], v[156:157] op_sel_hi:[1,0]
	v_exp_f32_e32 v152, v152
	v_exp_f32_e32 v153, v153
	v_exp_f32_e32 v154, v154
	v_exp_f32_e32 v155, v155
	v_pk_mul_f32 v[26:27], v[30:31], v[26:27]
	v_pk_mul_f32 v[28:29], v[32:33], v[28:29]
	v_pk_add_f32 v[152:153], v[152:153], v[166:167] op_sel_hi:[1,0]
	v_pk_add_f32 v[154:155], v[154:155], v[166:167] op_sel_hi:[1,0]
	v_rcp_f32_e32 v152, v152
	v_rcp_f32_e32 v153, v153
	v_rcp_f32_e32 v154, v154
	v_rcp_f32_e32 v155, v155
	v_pk_mul_f32 v[152:153], v[152:153], v[156:157] op_sel:[0,1]
	v_pk_mul_f32 v[154:155], v[154:155], v[156:157] op_sel:[0,1]
	v_pk_mul_f32 v[26:27], v[26:27], v[152:153]
	v_pk_mul_f32 v[28:29], v[28:29], v[154:155]
	v_pk_mul_f32 v[152:153], v[22:23], v[156:157] op_sel_hi:[1,0]
	v_pk_mul_f32 v[154:155], v[24:25], v[156:157] op_sel_hi:[1,0]
	v_exp_f32_e32 v152, v152
	v_exp_f32_e32 v153, v153
	v_exp_f32_e32 v154, v154
	v_exp_f32_e32 v155, v155
	v_pk_mul_f32 v[18:19], v[22:23], v[18:19]
	v_pk_mul_f32 v[20:21], v[24:25], v[20:21]
	v_pk_add_f32 v[152:153], v[152:153], v[166:167] op_sel_hi:[1,0]
	v_pk_add_f32 v[154:155], v[154:155], v[166:167] op_sel_hi:[1,0]
	v_rcp_f32_e32 v152, v152
	v_rcp_f32_e32 v153, v153
	v_rcp_f32_e32 v154, v154
	v_rcp_f32_e32 v155, v155
	v_pk_mul_f32 v[152:153], v[152:153], v[156:157] op_sel:[0,1]
	v_pk_mul_f32 v[154:155], v[154:155], v[156:157] op_sel:[0,1]
	v_pk_mul_f32 v[18:19], v[18:19], v[152:153]
	v_pk_mul_f32 v[20:21], v[20:21], v[154:155]
	v_cvt_pk_bf16_f32 v30, v26, v27
	v_cvt_pk_bf16_f32 v31, v28, v29
	v_cvt_pk_bf16_f32 v32, v18, v19
	v_cvt_pk_bf16_f32 v33, v20, v21
	v_add_u32_e32 v142, 0x1b8000, v143
	global_store_dwordx4 v142, v[30:33], s[10:11]
	v_mul_f32_e32 v156, 0xbfb8aa3b, v144
	v_mul_f32_e32 v157, v144, v144
	v_pk_mul_f32 v[152:153], v[14:15], v[156:157] op_sel_hi:[1,0]
	v_pk_mul_f32 v[154:155], v[16:17], v[156:157] op_sel_hi:[1,0]
	v_exp_f32_e32 v152, v152
	v_exp_f32_e32 v153, v153
	v_exp_f32_e32 v154, v154
	v_exp_f32_e32 v155, v155
	v_pk_mul_f32 v[10:11], v[14:15], v[10:11]
	v_pk_mul_f32 v[12:13], v[16:17], v[12:13]
	v_pk_add_f32 v[152:153], v[152:153], v[166:167] op_sel_hi:[1,0]
	v_pk_add_f32 v[154:155], v[154:155], v[166:167] op_sel_hi:[1,0]
	v_rcp_f32_e32 v152, v152
	v_rcp_f32_e32 v153, v153
	v_rcp_f32_e32 v154, v154
	v_rcp_f32_e32 v155, v155
	v_pk_mul_f32 v[152:153], v[152:153], v[156:157] op_sel:[0,1]
	v_pk_mul_f32 v[154:155], v[154:155], v[156:157] op_sel:[0,1]
	v_pk_mul_f32 v[10:11], v[10:11], v[152:153]
	v_pk_mul_f32 v[12:13], v[12:13], v[154:155]
	v_pk_mul_f32 v[152:153], v[6:7], v[156:157] op_sel_hi:[1,0]
	v_pk_mul_f32 v[154:155], v[8:9], v[156:157] op_sel_hi:[1,0]
	v_exp_f32_e32 v152, v152
	v_exp_f32_e32 v153, v153
	v_exp_f32_e32 v154, v154
	v_exp_f32_e32 v155, v155
	v_pk_mul_f32 v[2:3], v[6:7], v[2:3]
	v_pk_mul_f32 v[4:5], v[8:9], v[4:5]
	v_pk_add_f32 v[152:153], v[152:153], v[166:167] op_sel_hi:[1,0]
	v_pk_add_f32 v[154:155], v[154:155], v[166:167] op_sel_hi:[1,0]
	v_rcp_f32_e32 v152, v152
	v_rcp_f32_e32 v153, v153
	v_rcp_f32_e32 v154, v154
	v_rcp_f32_e32 v155, v155
	v_pk_mul_f32 v[152:153], v[152:153], v[156:157] op_sel:[0,1]
	v_pk_mul_f32 v[154:155], v[154:155], v[156:157] op_sel:[0,1]
	v_pk_mul_f32 v[2:3], v[2:3], v[152:153]
	v_pk_mul_f32 v[4:5], v[4:5], v[154:155]
	v_cvt_pk_bf16_f32 v14, v10, v11
	v_cvt_pk_bf16_f32 v15, v12, v13
	v_cvt_pk_bf16_f32 v16, v2, v3
	v_cvt_pk_bf16_f32 v17, v4, v5
	v_add_u32_e32 v142, 0x1e4000, v143
	global_store_dwordx4 v142, v[14:17], s[10:11]
	s_andn2_b64 vcc, exec, s[40:41]
	s_mov_b64 s[16:17], -1
	s_cbranch_vccnz .LBB0_655
	s_andn2_b64 vcc, exec, s[6:7]
	s_cbranch_vccnz .LBB0_654
	s_barrier
	s_branch .LBB0_654
